# S5 scan (both passes): B-projection tile transpose done in registers with v_permlane16/32_swap instead of LDS write/read round trip; pass-1 loop hand-written; pass-2 C-stage reads batched; prologue lo
# speedup vs baseline: 1.0039x; 1.0039x over previous
.LBB0_848:
	v_cndmask_b32_e64 v184, v80, 0, s[10:11]
	v_cndmask_b32_e64 v185, v81, 0, s[10:11]
	v_cndmask_b32_e64 v186, v82, 0, s[10:11]
	v_cndmask_b32_e64 v187, v83, 0, s[10:11]
	s_nop 1
	v_mfma_f32_16x16x32_bf16 v[188:191], v[184:187], v[0:3], 0
	v_mfma_f32_16x16x32_bf16 v[192:195], v[184:187], v[4:7], 0
	v_mfma_f32_16x16x32_bf16 v[196:199], v[184:187], v[8:11], 0
	v_mfma_f32_16x16x32_bf16 v[200:203], v[184:187], v[12:15], 0
	v_mfma_f32_16x16x32_bf16 v[204:207], v[184:187], v[16:19], 0
	v_mfma_f32_16x16x32_bf16 v[208:211], v[184:187], v[20:23], 0
	v_mfma_f32_16x16x32_bf16 v[212:215], v[184:187], v[24:27], 0
	v_mfma_f32_16x16x32_bf16 v[216:219], v[184:187], v[28:31], 0
	s_nop 7
	v_permlane16_swap_b32_e32 v188, v192
	v_permlane16_swap_b32_e32 v189, v193
	v_permlane16_swap_b32_e32 v190, v194
	v_permlane16_swap_b32_e32 v191, v195
	v_permlane16_swap_b32_e32 v196, v200
	v_permlane16_swap_b32_e32 v197, v201
	v_permlane16_swap_b32_e32 v198, v202
	v_permlane16_swap_b32_e32 v199, v203
	v_permlane16_swap_b32_e32 v204, v208
	v_permlane16_swap_b32_e32 v205, v209
	v_permlane16_swap_b32_e32 v206, v210
	v_permlane16_swap_b32_e32 v207, v211
	v_permlane16_swap_b32_e32 v212, v216
	v_permlane16_swap_b32_e32 v213, v217
	v_permlane16_swap_b32_e32 v214, v218
	v_permlane16_swap_b32_e32 v215, v219
	v_permlane32_swap_b32_e32 v188, v196
	v_permlane32_swap_b32_e32 v189, v197
	v_permlane32_swap_b32_e32 v190, v198
	v_permlane32_swap_b32_e32 v191, v199
	v_permlane32_swap_b32_e32 v192, v200
	v_permlane32_swap_b32_e32 v193, v201
	v_permlane32_swap_b32_e32 v194, v202
	v_permlane32_swap_b32_e32 v195, v203
	v_permlane32_swap_b32_e32 v204, v212
	v_permlane32_swap_b32_e32 v205, v213
	v_permlane32_swap_b32_e32 v206, v214
	v_permlane32_swap_b32_e32 v207, v215
	v_permlane32_swap_b32_e32 v208, v216
	v_permlane32_swap_b32_e32 v209, v217
	v_permlane32_swap_b32_e32 v210, v218
	v_permlane32_swap_b32_e32 v211, v219
	s_nop 1
	v_fma_f32 v184, -v132, v89, v188
	v_fma_f32 v185, v132, v88, v204
	v_fma_f32 v88, v128, v88, v184
	v_fma_f32 v89, v128, v89, v185
	v_fma_f32 v184, -v132, v89, v189
	v_fma_f32 v185, v132, v88, v205
	v_fma_f32 v88, v128, v88, v184
	v_fma_f32 v89, v128, v89, v185
	v_fma_f32 v184, -v132, v89, v190
	v_fma_f32 v185, v132, v88, v206
	v_fma_f32 v88, v128, v88, v184
	v_fma_f32 v89, v128, v89, v185
	v_fma_f32 v184, -v132, v89, v191
	v_fma_f32 v185, v132, v88, v207
	v_fma_f32 v88, v128, v88, v184
	v_fma_f32 v89, v128, v89, v185
	v_fma_f32 v184, -v132, v89, v192
	v_fma_f32 v185, v132, v88, v208
	v_fma_f32 v88, v128, v88, v184
	v_fma_f32 v89, v128, v89, v185
	v_fma_f32 v184, -v132, v89, v193
	v_fma_f32 v185, v132, v88, v209
	v_fma_f32 v88, v128, v88, v184
	v_fma_f32 v89, v128, v89, v185
	v_fma_f32 v184, -v132, v89, v194
	v_fma_f32 v185, v132, v88, v210
	v_fma_f32 v88, v128, v88, v184
	v_fma_f32 v89, v128, v89, v185
	v_fma_f32 v184, -v132, v89, v195
	v_fma_f32 v185, v132, v88, v211
	v_fma_f32 v88, v128, v88, v184
	v_fma_f32 v89, v128, v89, v185
	v_fma_f32 v184, -v132, v89, v196
	v_fma_f32 v185, v132, v88, v212
	v_fma_f32 v88, v128, v88, v184
	v_fma_f32 v89, v128, v89, v185
	v_fma_f32 v184, -v132, v89, v197
	v_fma_f32 v185, v132, v88, v213
	v_fma_f32 v88, v128, v88, v184
	v_fma_f32 v89, v128, v89, v185
	v_fma_f32 v184, -v132, v89, v198
	v_fma_f32 v185, v132, v88, v214
	v_fma_f32 v88, v128, v88, v184
	v_fma_f32 v89, v128, v89, v185
	v_fma_f32 v184, -v132, v89, v199
	v_fma_f32 v185, v132, v88, v215
	v_fma_f32 v88, v128, v88, v184
	v_fma_f32 v89, v128, v89, v185
	v_fma_f32 v184, -v132, v89, v200
	v_fma_f32 v185, v132, v88, v216
	v_fma_f32 v88, v128, v88, v184
	v_fma_f32 v89, v128, v89, v185
	v_fma_f32 v184, -v132, v89, v201
	v_fma_f32 v185, v132, v88, v217
	v_fma_f32 v88, v128, v88, v184
	v_fma_f32 v89, v128, v89, v185
	v_fma_f32 v184, -v132, v89, v202
	v_fma_f32 v185, v132, v88, v218
	v_fma_f32 v88, v128, v88, v184
	v_fma_f32 v89, v128, v89, v185
	v_fma_f32 v184, -v132, v89, v203
	v_fma_f32 v185, v132, v88, v219
	v_fma_f32 v88, v128, v88, v184
	v_fma_f32 v89, v128, v89, v185
	v_cndmask_b32_e64 v184, v76, 0, s[10:11]
	v_cndmask_b32_e64 v185, v77, 0, s[10:11]
	v_cndmask_b32_e64 v186, v78, 0, s[10:11]
	v_cndmask_b32_e64 v187, v79, 0, s[10:11]
	s_nop 1
	v_mfma_f32_16x16x32_bf16 v[188:191], v[184:187], v[0:3], 0
	v_mfma_f32_16x16x32_bf16 v[192:195], v[184:187], v[4:7], 0
	v_mfma_f32_16x16x32_bf16 v[196:199], v[184:187], v[8:11], 0
	v_mfma_f32_16x16x32_bf16 v[200:203], v[184:187], v[12:15], 0
	v_mfma_f32_16x16x32_bf16 v[204:207], v[184:187], v[16:19], 0
	v_mfma_f32_16x16x32_bf16 v[208:211], v[184:187], v[20:23], 0
	v_mfma_f32_16x16x32_bf16 v[212:215], v[184:187], v[24:27], 0
	v_mfma_f32_16x16x32_bf16 v[216:219], v[184:187], v[28:31], 0
	s_nop 7
	v_permlane16_swap_b32_e32 v188, v192
	v_permlane16_swap_b32_e32 v189, v193
	v_permlane16_swap_b32_e32 v190, v194
	v_permlane16_swap_b32_e32 v191, v195
	v_permlane16_swap_b32_e32 v196, v200
	v_permlane16_swap_b32_e32 v197, v201
	v_permlane16_swap_b32_e32 v198, v202
	v_permlane16_swap_b32_e32 v199, v203
	v_permlane16_swap_b32_e32 v204, v208
	v_permlane16_swap_b32_e32 v205, v209
	v_permlane16_swap_b32_e32 v206, v210
	v_permlane16_swap_b32_e32 v207, v211
	v_permlane16_swap_b32_e32 v212, v216
	v_permlane16_swap_b32_e32 v213, v217
	v_permlane16_swap_b32_e32 v214, v218
	v_permlane16_swap_b32_e32 v215, v219
	v_permlane32_swap_b32_e32 v188, v196
	v_permlane32_swap_b32_e32 v189, v197
	v_permlane32_swap_b32_e32 v190, v198
	v_permlane32_swap_b32_e32 v191, v199
	v_permlane32_swap_b32_e32 v192, v200
	v_permlane32_swap_b32_e32 v193, v201
	v_permlane32_swap_b32_e32 v194, v202
	v_permlane32_swap_b32_e32 v195, v203
	v_permlane32_swap_b32_e32 v204, v212
	v_permlane32_swap_b32_e32 v205, v213
	v_permlane32_swap_b32_e32 v206, v214
	v_permlane32_swap_b32_e32 v207, v215
	v_permlane32_swap_b32_e32 v208, v216
	v_permlane32_swap_b32_e32 v209, v217
	v_permlane32_swap_b32_e32 v210, v218
	v_permlane32_swap_b32_e32 v211, v219
	s_nop 1
	v_fma_f32 v184, -v132, v89, v188
	v_fma_f32 v185, v132, v88, v204
	v_fma_f32 v88, v128, v88, v184
	v_fma_f32 v89, v128, v89, v185
	v_fma_f32 v184, -v132, v89, v189
	v_fma_f32 v185, v132, v88, v205
	v_fma_f32 v88, v128, v88, v184
	v_fma_f32 v89, v128, v89, v185
	v_fma_f32 v184, -v132, v89, v190
	v_fma_f32 v185, v132, v88, v206
	v_fma_f32 v88, v128, v88, v184
	v_fma_f32 v89, v128, v89, v185
	v_fma_f32 v184, -v132, v89, v191
	v_fma_f32 v185, v132, v88, v207
	v_fma_f32 v88, v128, v88, v184
	v_fma_f32 v89, v128, v89, v185
	v_fma_f32 v184, -v132, v89, v192
	v_fma_f32 v185, v132, v88, v208
	v_fma_f32 v88, v128, v88, v184
	v_fma_f32 v89, v128, v89, v185
	v_fma_f32 v184, -v132, v89, v193
	v_fma_f32 v185, v132, v88, v209
	v_fma_f32 v88, v128, v88, v184
	v_fma_f32 v89, v128, v89, v185
	v_fma_f32 v184, -v132, v89, v194
	v_fma_f32 v185, v132, v88, v210
	v_fma_f32 v88, v128, v88, v184
	v_fma_f32 v89, v128, v89, v185
	v_fma_f32 v184, -v132, v89, v195
	v_fma_f32 v185, v132, v88, v211
	v_fma_f32 v88, v128, v88, v184
	v_fma_f32 v89, v128, v89, v185
	v_fma_f32 v184, -v132, v89, v196
	v_fma_f32 v185, v132, v88, v212
	v_fma_f32 v88, v128, v88, v184
	v_fma_f32 v89, v128, v89, v185
	v_fma_f32 v184, -v132, v89, v197
	v_fma_f32 v185, v132, v88, v213
	v_fma_f32 v88, v128, v88, v184
	v_fma_f32 v89, v128, v89, v185
	v_fma_f32 v184, -v132, v89, v198
	v_fma_f32 v185, v132, v88, v214
	v_fma_f32 v88, v128, v88, v184
	v_fma_f32 v89, v128, v89, v185
	v_fma_f32 v184, -v132, v89, v199
	v_fma_f32 v185, v132, v88, v215
	v_fma_f32 v88, v128, v88, v184
	v_fma_f32 v89, v128, v89, v185
	v_fma_f32 v184, -v132, v89, v200
	v_fma_f32 v185, v132, v88, v216
	v_fma_f32 v88, v128, v88, v184
	v_fma_f32 v89, v128, v89, v185
	v_fma_f32 v184, -v132, v89, v201
	v_fma_f32 v185, v132, v88, v217
	v_fma_f32 v88, v128, v88, v184
	v_fma_f32 v89, v128, v89, v185
	v_fma_f32 v184, -v132, v89, v202
	v_fma_f32 v185, v132, v88, v218
	v_fma_f32 v88, v128, v88, v184
	v_fma_f32 v89, v128, v89, v185
	v_fma_f32 v184, -v132, v89, v203
	v_fma_f32 v185, v132, v88, v219
	v_fma_f32 v88, v128, v88, v184
	v_fma_f32 v89, v128, v89, v185
	v_cndmask_b32_e64 v184, v72, 0, s[10:11]
	v_cndmask_b32_e64 v185, v73, 0, s[10:11]
	v_cndmask_b32_e64 v186, v74, 0, s[10:11]
	v_cndmask_b32_e64 v187, v75, 0, s[10:11]
	s_nop 1
	v_mfma_f32_16x16x32_bf16 v[188:191], v[184:187], v[0:3], 0
	v_mfma_f32_16x16x32_bf16 v[192:195], v[184:187], v[4:7], 0
	v_mfma_f32_16x16x32_bf16 v[196:199], v[184:187], v[8:11], 0
	v_mfma_f32_16x16x32_bf16 v[200:203], v[184:187], v[12:15], 0
	v_mfma_f32_16x16x32_bf16 v[204:207], v[184:187], v[16:19], 0
	v_mfma_f32_16x16x32_bf16 v[208:211], v[184:187], v[20:23], 0
	v_mfma_f32_16x16x32_bf16 v[212:215], v[184:187], v[24:27], 0
	v_mfma_f32_16x16x32_bf16 v[216:219], v[184:187], v[28:31], 0
	s_nop 7
	v_permlane16_swap_b32_e32 v188, v192
	v_permlane16_swap_b32_e32 v189, v193
	v_permlane16_swap_b32_e32 v190, v194
	v_permlane16_swap_b32_e32 v191, v195
	v_permlane16_swap_b32_e32 v196, v200
	v_permlane16_swap_b32_e32 v197, v201
	v_permlane16_swap_b32_e32 v198, v202
	v_permlane16_swap_b32_e32 v199, v203
	v_permlane16_swap_b32_e32 v204, v208
	v_permlane16_swap_b32_e32 v205, v209
	v_permlane16_swap_b32_e32 v206, v210
	v_permlane16_swap_b32_e32 v207, v211
	v_permlane16_swap_b32_e32 v212, v216
	v_permlane16_swap_b32_e32 v213, v217
	v_permlane16_swap_b32_e32 v214, v218
	v_permlane16_swap_b32_e32 v215, v219
	v_permlane32_swap_b32_e32 v188, v196
	v_permlane32_swap_b32_e32 v189, v197
	v_permlane32_swap_b32_e32 v190, v198
	v_permlane32_swap_b32_e32 v191, v199
	v_permlane32_swap_b32_e32 v192, v200
	v_permlane32_swap_b32_e32 v193, v201
	v_permlane32_swap_b32_e32 v194, v202
	v_permlane32_swap_b32_e32 v195, v203
	v_permlane32_swap_b32_e32 v204, v212
	v_permlane32_swap_b32_e32 v205, v213
	v_permlane32_swap_b32_e32 v206, v214
	v_permlane32_swap_b32_e32 v207, v215
	v_permlane32_swap_b32_e32 v208, v216
	v_permlane32_swap_b32_e32 v209, v217
	v_permlane32_swap_b32_e32 v210, v218
	v_permlane32_swap_b32_e32 v211, v219
	s_nop 1
	v_fma_f32 v184, -v132, v89, v188
	v_fma_f32 v185, v132, v88, v204
	v_fma_f32 v88, v128, v88, v184
	v_fma_f32 v89, v128, v89, v185
	v_fma_f32 v184, -v132, v89, v189
	v_fma_f32 v185, v132, v88, v205
	v_fma_f32 v88, v128, v88, v184
	v_fma_f32 v89, v128, v89, v185
	v_fma_f32 v184, -v132, v89, v190
	v_fma_f32 v185, v132, v88, v206
	v_fma_f32 v88, v128, v88, v184
	v_fma_f32 v89, v128, v89, v185
	v_fma_f32 v184, -v132, v89, v191
	v_fma_f32 v185, v132, v88, v207
	v_fma_f32 v88, v128, v88, v184
	v_fma_f32 v89, v128, v89, v185
	v_fma_f32 v184, -v132, v89, v192
	v_fma_f32 v185, v132, v88, v208
	v_fma_f32 v88, v128, v88, v184
	v_fma_f32 v89, v128, v89, v185
	v_fma_f32 v184, -v132, v89, v193
	v_fma_f32 v185, v132, v88, v209
	v_fma_f32 v88, v128, v88, v184
	v_fma_f32 v89, v128, v89, v185
	v_fma_f32 v184, -v132, v89, v194
	v_fma_f32 v185, v132, v88, v210
	v_fma_f32 v88, v128, v88, v184
	v_fma_f32 v89, v128, v89, v185
	v_fma_f32 v184, -v132, v89, v195
	v_fma_f32 v185, v132, v88, v211
	v_fma_f32 v88, v128, v88, v184
	v_fma_f32 v89, v128, v89, v185
	v_fma_f32 v184, -v132, v89, v196
	v_fma_f32 v185, v132, v88, v212
	v_fma_f32 v88, v128, v88, v184
	v_fma_f32 v89, v128, v89, v185
	v_fma_f32 v184, -v132, v89, v197
	v_fma_f32 v185, v132, v88, v213
	v_fma_f32 v88, v128, v88, v184
	v_fma_f32 v89, v128, v89, v185
	v_fma_f32 v184, -v132, v89, v198
	v_fma_f32 v185, v132, v88, v214
	v_fma_f32 v88, v128, v88, v184
	v_fma_f32 v89, v128, v89, v185
	v_fma_f32 v184, -v132, v89, v199
	v_fma_f32 v185, v132, v88, v215
	v_fma_f32 v88, v128, v88, v184
	v_fma_f32 v89, v128, v89, v185
	v_fma_f32 v184, -v132, v89, v200
	v_fma_f32 v185, v132, v88, v216
	v_fma_f32 v88, v128, v88, v184
	v_fma_f32 v89, v128, v89, v185
	v_fma_f32 v184, -v132, v89, v201
	v_fma_f32 v185, v132, v88, v217
	v_fma_f32 v88, v128, v88, v184
	v_fma_f32 v89, v128, v89, v185
	v_fma_f32 v184, -v132, v89, v202
	v_fma_f32 v185, v132, v88, v218
	v_fma_f32 v88, v128, v88, v184
	v_fma_f32 v89, v128, v89, v185
	v_fma_f32 v184, -v132, v89, v203
	v_fma_f32 v185, v132, v88, v219
	v_fma_f32 v88, v128, v88, v184
	v_fma_f32 v89, v128, v89, v185
	v_cndmask_b32_e64 v184, v68, 0, s[10:11]
	v_cndmask_b32_e64 v185, v69, 0, s[10:11]
	v_cndmask_b32_e64 v186, v70, 0, s[10:11]
	v_cndmask_b32_e64 v187, v71, 0, s[10:11]
	s_nop 1
	v_mfma_f32_16x16x32_bf16 v[188:191], v[184:187], v[0:3], 0
	v_mfma_f32_16x16x32_bf16 v[192:195], v[184:187], v[4:7], 0
	v_mfma_f32_16x16x32_bf16 v[196:199], v[184:187], v[8:11], 0
	v_mfma_f32_16x16x32_bf16 v[200:203], v[184:187], v[12:15], 0
	v_mfma_f32_16x16x32_bf16 v[204:207], v[184:187], v[16:19], 0
	v_mfma_f32_16x16x32_bf16 v[208:211], v[184:187], v[20:23], 0
	v_mfma_f32_16x16x32_bf16 v[212:215], v[184:187], v[24:27], 0
	v_mfma_f32_16x16x32_bf16 v[216:219], v[184:187], v[28:31], 0
	s_nop 7
	v_permlane16_swap_b32_e32 v188, v192
	v_permlane16_swap_b32_e32 v189, v193
	v_permlane16_swap_b32_e32 v190, v194
	v_permlane16_swap_b32_e32 v191, v195
	v_permlane16_swap_b32_e32 v196, v200
	v_permlane16_swap_b32_e32 v197, v201
	v_permlane16_swap_b32_e32 v198, v202
	v_permlane16_swap_b32_e32 v199, v203
	v_permlane16_swap_b32_e32 v204, v208
	v_permlane16_swap_b32_e32 v205, v209
	v_permlane16_swap_b32_e32 v206, v210
	v_permlane16_swap_b32_e32 v207, v211
	v_permlane16_swap_b32_e32 v212, v216
	v_permlane16_swap_b32_e32 v213, v217
	v_permlane16_swap_b32_e32 v214, v218
	v_permlane16_swap_b32_e32 v215, v219
	v_permlane32_swap_b32_e32 v188, v196
	v_permlane32_swap_b32_e32 v189, v197
	v_permlane32_swap_b32_e32 v190, v198
	v_permlane32_swap_b32_e32 v191, v199
	v_permlane32_swap_b32_e32 v192, v200
	v_permlane32_swap_b32_e32 v193, v201
	v_permlane32_swap_b32_e32 v194, v202
	v_permlane32_swap_b32_e32 v195, v203
	v_permlane32_swap_b32_e32 v204, v212
	v_permlane32_swap_b32_e32 v205, v213
	v_permlane32_swap_b32_e32 v206, v214
	v_permlane32_swap_b32_e32 v207, v215
	v_permlane32_swap_b32_e32 v208, v216
	v_permlane32_swap_b32_e32 v209, v217
	v_permlane32_swap_b32_e32 v210, v218
	v_permlane32_swap_b32_e32 v211, v219
	s_nop 1
	v_fma_f32 v184, -v132, v89, v188
	v_fma_f32 v185, v132, v88, v204
	v_fma_f32 v88, v128, v88, v184
	v_fma_f32 v89, v128, v89, v185
	v_fma_f32 v184, -v132, v89, v189
	v_fma_f32 v185, v132, v88, v205
	v_fma_f32 v88, v128, v88, v184
	v_fma_f32 v89, v128, v89, v185
	v_fma_f32 v184, -v132, v89, v190
	v_fma_f32 v185, v132, v88, v206
	v_fma_f32 v88, v128, v88, v184
	v_fma_f32 v89, v128, v89, v185
	v_fma_f32 v184, -v132, v89, v191
	v_fma_f32 v185, v132, v88, v207
	v_fma_f32 v88, v128, v88, v184
	v_fma_f32 v89, v128, v89, v185
	v_fma_f32 v184, -v132, v89, v192
	v_fma_f32 v185, v132, v88, v208
	v_fma_f32 v88, v128, v88, v184
	v_fma_f32 v89, v128, v89, v185
	v_fma_f32 v184, -v132, v89, v193
	v_fma_f32 v185, v132, v88, v209
	v_fma_f32 v88, v128, v88, v184
	v_fma_f32 v89, v128, v89, v185
	v_fma_f32 v184, -v132, v89, v194
	v_fma_f32 v185, v132, v88, v210
	v_fma_f32 v88, v128, v88, v184
	v_fma_f32 v89, v128, v89, v185
	v_fma_f32 v184, -v132, v89, v195
	v_fma_f32 v185, v132, v88, v211
	v_fma_f32 v88, v128, v88, v184
	v_fma_f32 v89, v128, v89, v185
	v_fma_f32 v184, -v132, v89, v196
	v_fma_f32 v185, v132, v88, v212
	v_fma_f32 v88, v128, v88, v184
	v_fma_f32 v89, v128, v89, v185
	v_fma_f32 v184, -v132, v89, v197
	v_fma_f32 v185, v132, v88, v213
	v_fma_f32 v88, v128, v88, v184
	v_fma_f32 v89, v128, v89, v185
	v_fma_f32 v184, -v132, v89, v198
	v_fma_f32 v185, v132, v88, v214
	v_fma_f32 v88, v128, v88, v184
	v_fma_f32 v89, v128, v89, v185
	v_fma_f32 v184, -v132, v89, v199
	v_fma_f32 v185, v132, v88, v215
	v_fma_f32 v88, v128, v88, v184
	v_fma_f32 v89, v128, v89, v185
	v_fma_f32 v184, -v132, v89, v200
	v_fma_f32 v185, v132, v88, v216
	v_fma_f32 v88, v128, v88, v184
	v_fma_f32 v89, v128, v89, v185
	v_fma_f32 v184, -v132, v89, v201
	v_fma_f32 v185, v132, v88, v217
	v_fma_f32 v88, v128, v88, v184
	v_fma_f32 v89, v128, v89, v185
	v_fma_f32 v184, -v132, v89, v202
	v_fma_f32 v185, v132, v88, v218
	v_fma_f32 v88, v128, v88, v184
	v_fma_f32 v89, v128, v89, v185
	v_fma_f32 v184, -v132, v89, v203
	v_fma_f32 v185, v132, v88, v219
	v_fma_f32 v88, v128, v88, v184
	v_fma_f32 v89, v128, v89, v185
	s_add_i32 s34, s34, 1
	s_add_u32 s30, s30, 0x40000
	s_addc_u32 s31, s31, 0
	s_cmp_eq_u32 s30, 0x200000
	s_cbranch_scc1 .LBB0_850
	s_waitcnt vmcnt(0)
	v_mov_b64_e32 v[70:71], v[66:67]
	v_mov_b64_e32 v[74:75], v[62:63]
	v_mov_b64_e32 v[78:79], v[58:59]
	v_mov_b64_e32 v[82:83], v[54:55]
	v_mov_b64_e32 v[68:69], v[64:65]
	v_mov_b64_e32 v[72:73], v[60:61]
	v_mov_b64_e32 v[76:77], v[56:57]
	v_mov_b64_e32 v[80:81], v[52:53]
	s_cmp_gt_u32 s34, 6
	s_cbranch_scc0 .LBB0_847
	s_branch .LBB0_848

.LBB0_873:
	v_cndmask_b32_e64 v93, v83, 0, s[10:11]
	v_cndmask_b32_e64 v92, v82, 0, s[10:11]
	v_cndmask_b32_e64 v91, v81, 0, s[10:11]
	v_cndmask_b32_e64 v90, v80, 0, s[10:11]
	v_add_u32_e32 v81, v139, v141
	v_add_u32_e32 v83, v139, v142
	v_mfma_f32_16x16x32_bf16 v[192:195], v[90:93], v[0:3], 0
	v_add_u32_e32 v88, v139, v143
	v_add_u32_e32 v82, s86, v140
	v_mul_f32_e32 v80, v132, v87
	v_mfma_f32_16x16x32_bf16 v[196:199], v[90:93], v[4:7], 0
	v_mul_f32_e32 v87, v128, v87
	v_fma_f32 v80, v128, v86, -v80
	v_fmac_f32_e32 v87, v132, v86
	v_mfma_f32_16x16x32_bf16 v[200:203], v[90:93], v[8:11], 0
	s_nop 2
	s_nop 2
	v_cndmask_b32_e64 v79, v79, 0, s[10:11]
	v_mfma_f32_16x16x32_bf16 v[204:207], v[90:93], v[12:15], 0
	v_cndmask_b32_e64 v78, v78, 0, s[10:11]
	v_cndmask_b32_e64 v77, v77, 0, s[10:11]
	v_cndmask_b32_e64 v76, v76, 0, s[10:11]
	v_mfma_f32_16x16x32_bf16 v[212:215], v[90:93], v[20:23], 0
	v_cndmask_b32_e64 v75, v75, 0, s[10:11]
	v_cndmask_b32_e64 v74, v74, 0, s[10:11]
	v_cndmask_b32_e64 v73, v73, 0, s[10:11]
	v_mfma_f32_16x16x32_bf16 v[208:211], v[90:93], v[16:19], 0
	s_nop 6
	v_mfma_f32_16x16x32_bf16 v[216:219], v[90:93], v[24:27], 0
	s_nop 6
	v_mfma_f32_16x16x32_bf16 v[220:223], v[90:93], v[28:31], 0
	v_cndmask_b32_e64 v72, v72, 0, s[10:11]
	v_cndmask_b32_e64 v71, v71, 0, s[10:11]
	v_cndmask_b32_e64 v70, v70, 0, s[10:11]
	v_mfma_f32_16x16x32_bf16 v[90:93], v[90:93], v[48:51], 0
	v_cndmask_b32_e64 v69, v69, 0, s[10:11]
	s_nop 2
	s_nop 7
	v_permlane16_swap_b32_e32 v192, v196
	v_permlane16_swap_b32_e32 v193, v197
	v_permlane16_swap_b32_e32 v194, v198
	v_permlane16_swap_b32_e32 v195, v199
	v_permlane16_swap_b32_e32 v200, v204
	v_permlane16_swap_b32_e32 v201, v205
	v_permlane16_swap_b32_e32 v202, v206
	v_permlane16_swap_b32_e32 v203, v207
	v_permlane16_swap_b32_e32 v208, v212
	v_permlane16_swap_b32_e32 v209, v213
	v_permlane16_swap_b32_e32 v210, v214
	v_permlane16_swap_b32_e32 v211, v215
	v_permlane16_swap_b32_e32 v216, v220
	v_permlane16_swap_b32_e32 v217, v221
	v_permlane16_swap_b32_e32 v218, v222
	v_permlane16_swap_b32_e32 v219, v223
	v_permlane32_swap_b32_e32 v192, v200
	v_permlane32_swap_b32_e32 v193, v201
	v_permlane32_swap_b32_e32 v194, v202
	v_permlane32_swap_b32_e32 v195, v203
	v_permlane32_swap_b32_e32 v196, v204
	v_permlane32_swap_b32_e32 v197, v205
	v_permlane32_swap_b32_e32 v198, v206
	v_permlane32_swap_b32_e32 v199, v207
	v_permlane32_swap_b32_e32 v208, v216
	v_permlane32_swap_b32_e32 v209, v217
	v_permlane32_swap_b32_e32 v210, v218
	v_permlane32_swap_b32_e32 v211, v219
	v_permlane32_swap_b32_e32 v212, v220
	v_permlane32_swap_b32_e32 v213, v221
	v_permlane32_swap_b32_e32 v214, v222
	v_permlane32_swap_b32_e32 v215, v223
	s_waitcnt lgkmcnt(7)
	v_add_f32_e32 v80, v80, v192
	s_waitcnt lgkmcnt(3)
	v_add_f32_e32 v86, v87, v208
	v_cvt_pk_bf16_f32 v87, v80, v86
	ds_write_b32 v149, v87 offset:10240
	v_mul_f32_e32 v87, v132, v86
	v_mul_f32_e32 v86, v128, v86
	v_fma_f32 v87, v128, v80, -v87
	v_fmac_f32_e32 v86, v132, v80
	v_add_f32_e32 v87, v193, v87
	v_add_f32_e32 v80, v209, v86
	v_cvt_pk_bf16_f32 v86, v87, v80
	ds_write_b32 v149, v86 offset:10512
	v_mul_f32_e32 v86, v132, v80
	v_mul_f32_e32 v80, v128, v80
	v_fma_f32 v86, v128, v87, -v86
	v_fmac_f32_e32 v80, v132, v87
	v_add_f32_e32 v86, v194, v86
	v_add_f32_e32 v80, v210, v80
	v_cvt_pk_bf16_f32 v87, v86, v80
	ds_write_b32 v149, v87 offset:10784
	v_mul_f32_e32 v87, v132, v80
	v_mul_f32_e32 v80, v128, v80
	v_fma_f32 v87, v128, v86, -v87
	v_fmac_f32_e32 v80, v132, v86
	v_add_f32_e32 v87, v195, v87
	v_add_f32_e32 v80, v211, v80
	v_cvt_pk_bf16_f32 v86, v87, v80
	ds_write_b32 v149, v86 offset:11056
	v_mul_f32_e32 v86, v132, v80
	v_mul_f32_e32 v80, v128, v80
	v_fma_f32 v86, v128, v87, -v86
	v_fmac_f32_e32 v80, v132, v87
	v_add_f32_e32 v86, v196, v86
	s_waitcnt lgkmcnt(6)
	v_add_f32_e32 v80, v212, v80
	v_cvt_pk_bf16_f32 v87, v86, v80
	ds_write_b32 v149, v87 offset:11328
	v_mul_f32_e32 v87, v132, v80
	v_mul_f32_e32 v80, v128, v80
	v_fma_f32 v87, v128, v86, -v87
	v_fmac_f32_e32 v80, v132, v86
	v_add_f32_e32 v87, v197, v87
	v_add_f32_e32 v80, v213, v80
	v_cvt_pk_bf16_f32 v86, v87, v80
	ds_write_b32 v149, v86 offset:11600
	v_mul_f32_e32 v86, v132, v80
	v_mul_f32_e32 v80, v128, v80
	v_fma_f32 v86, v128, v87, -v86
	v_fmac_f32_e32 v80, v132, v87
	v_add_f32_e32 v86, v198, v86
	v_add_f32_e32 v80, v214, v80
	v_cvt_pk_bf16_f32 v87, v86, v80
	ds_write_b32 v149, v87 offset:11872
	v_mul_f32_e32 v87, v132, v80
	v_mul_f32_e32 v80, v128, v80
	v_fma_f32 v87, v128, v86, -v87
	v_fmac_f32_e32 v80, v132, v86
	v_add_f32_e32 v87, v199, v87
	v_add_f32_e32 v80, v215, v80
	v_cvt_pk_bf16_f32 v86, v87, v80
	ds_write_b32 v149, v86 offset:12144
	v_mul_f32_e32 v86, v132, v80
	v_mul_f32_e32 v80, v128, v80
	v_fma_f32 v86, v128, v87, -v86
	v_fmac_f32_e32 v80, v132, v87
	v_add_f32_e32 v86, v200, v86
	s_waitcnt lgkmcnt(9)
	v_add_f32_e32 v80, v216, v80
	v_cvt_pk_bf16_f32 v87, v86, v80
	ds_write_b32 v149, v87 offset:12416
	v_mul_f32_e32 v87, v132, v80
	v_mul_f32_e32 v80, v128, v80
	v_fma_f32 v87, v128, v86, -v87
	v_fmac_f32_e32 v80, v132, v86
	v_add_f32_e32 v87, v201, v87
	v_add_f32_e32 v80, v217, v80
	v_cvt_pk_bf16_f32 v86, v87, v80
	ds_write_b32 v149, v86 offset:12688
	v_mul_f32_e32 v86, v132, v80
	v_mul_f32_e32 v80, v128, v80
	v_fma_f32 v86, v128, v87, -v86
	v_fmac_f32_e32 v80, v132, v87
	v_add_f32_e32 v86, v202, v86
	v_add_f32_e32 v80, v218, v80
	v_cvt_pk_bf16_f32 v87, v86, v80
	ds_write_b32 v149, v87 offset:12960
	v_mul_f32_e32 v87, v132, v80
	v_mul_f32_e32 v80, v128, v80
	v_fma_f32 v87, v128, v86, -v87
	v_fmac_f32_e32 v80, v132, v86
	v_add_f32_e32 v87, v203, v87
	v_add_f32_e32 v80, v219, v80
	v_cvt_pk_bf16_f32 v86, v87, v80
	ds_write_b32 v149, v86 offset:13232
	v_mul_f32_e32 v86, v132, v80
	v_mul_f32_e32 v80, v128, v80
	v_fma_f32 v86, v128, v87, -v86
	v_fmac_f32_e32 v80, v132, v87
	v_add_f32_e32 v86, v204, v86
	s_waitcnt lgkmcnt(12)
	v_add_f32_e32 v80, v220, v80
	v_cvt_pk_bf16_f32 v87, v86, v80
	ds_write_b32 v149, v87 offset:13504
	v_mul_f32_e32 v87, v132, v80
	v_mul_f32_e32 v80, v128, v80
	v_fma_f32 v87, v128, v86, -v87
	v_fmac_f32_e32 v80, v132, v86
	v_add_f32_e32 v87, v205, v87
	v_add_f32_e32 v80, v221, v80
	v_cvt_pk_bf16_f32 v86, v87, v80
	ds_write_b32 v149, v86 offset:13776
	v_mul_f32_e32 v86, v132, v80
	v_mul_f32_e32 v80, v128, v80
	v_fma_f32 v86, v128, v87, -v86
	v_fmac_f32_e32 v80, v132, v87
	v_add_f32_e32 v86, v206, v86
	v_add_f32_e32 v80, v222, v80
	v_cvt_pk_bf16_f32 v87, v86, v80
	ds_write_b32 v149, v87 offset:14048
	v_mul_f32_e32 v87, v132, v80
	v_mul_f32_e32 v80, v128, v80
	v_fma_f32 v87, v128, v86, -v87
	v_fmac_f32_e32 v80, v132, v86
	v_add_f32_e32 v87, v207, v87
	v_add_f32_e32 v86, v223, v80
	v_cvt_pk_bf16_f32 v80, v87, v86
	ds_write_b32 v149, v80 offset:14320
	s_waitcnt lgkmcnt(0)
	v_add_u32_e32 v80, v150, v138
	ds_read_b128 v[94:97], v80 offset:10240
	ds_read_b128 v[98:101], v80 offset:10304
	ds_read_b128 v[184:187], v80 offset:10368
	ds_read_b128 v[188:191], v80 offset:10432
	s_waitcnt lgkmcnt(3)
	v_mfma_f32_16x16x32_bf16 v[90:93], v[94:97], v[32:35], v[90:93]
	v_cndmask_b32_e64 v68, v68, 0, s[10:11]
	s_add_u32 s30, s30, 0x40000
	s_waitcnt lgkmcnt(2)
	v_mfma_f32_16x16x32_bf16 v[90:93], v[98:101], v[36:39], v[90:93]
	s_addc_u32 s31, s31, 0
	s_cmp_eq_u32 s30, 0x240000
	s_waitcnt lgkmcnt(1)
	v_mfma_f32_16x16x32_bf16 v[90:93], v[184:187], v[40:43], v[90:93]
	s_cselect_b64 s[34:35], -1, 0
	s_waitcnt lgkmcnt(0)
	v_mfma_f32_16x16x32_bf16 v[90:93], v[188:191], v[44:47], v[90:93]
	v_mfma_f32_16x16x32_bf16 v[196:199], v[76:79], v[4:7], 0
	v_mfma_f32_16x16x32_bf16 v[200:203], v[76:79], v[8:11], 0
	s_nop 5
	v_mul_f32_e32 v89, 0x3d122279, v90
	v_fmaak_f32 v89, v90, v89, 0x3f4c422a
	v_mul_f32_e32 v89, v90, v89
	v_add_f32_e32 v89, v89, v89
	v_mul_f32_e32 v89, 0xbfb8aa3b, v89
	v_exp_f32_e32 v89, v89
	v_mul_f32_e32 v94, 0x3d122279, v91
	v_fmaak_f32 v94, v91, v94, 0x3f4c422a
	v_mul_f32_e32 v94, v91, v94
	v_add_f32_e32 v94, v94, v94
	v_mul_f32_e32 v94, 0xbfb8aa3b, v94
	v_add_f32_e32 v89, 1.0, v89
	v_exp_f32_e32 v94, v94
	v_rcp_f32_e32 v89, v89
	v_mfma_f32_16x16x32_bf16 v[204:207], v[76:79], v[12:15], 0
	v_add_f32_e32 v94, 1.0, v94
	v_mul_f32_e32 v89, v90, v89
	v_mul_f32_e32 v90, 0x3d122279, v92
	v_rcp_f32_e32 v94, v94
	v_fmaak_f32 v90, v92, v90, 0x3f4c422a
	v_mul_f32_e32 v90, v92, v90
	v_add_f32_e32 v90, v90, v90
	v_cvt_pk_bf16_f32 v89, v89, v89
	v_mul_f32_e32 v90, 0xbfb8aa3b, v90
	ds_write_b16 v160, v89 offset:14592
	v_mul_f32_e32 v89, v91, v94
	v_exp_f32_e32 v90, v90
	v_mul_f32_e32 v91, 0x3d122279, v93
	v_fmaak_f32 v91, v93, v91, 0x3f4c422a
	v_mul_f32_e32 v91, v93, v91
	v_add_f32_e32 v91, v91, v91
	v_add_f32_e32 v90, 1.0, v90
	v_mul_f32_e32 v91, 0xbfb8aa3b, v91
	v_rcp_f32_e32 v90, v90
	v_exp_f32_e32 v91, v91
	v_cvt_pk_bf16_f32 v89, v89, v89
	ds_write_b16 v160, v89 offset:14624
	v_mul_f32_e32 v89, v92, v90
	v_add_f32_e32 v90, 1.0, v91
	v_rcp_f32_e32 v90, v90
	v_mfma_f32_16x16x32_bf16 v[192:195], v[76:79], v[0:3], 0
	v_cvt_pk_bf16_f32 v89, v89, v89
	ds_write_b16 v160, v89 offset:14656
	v_mul_f32_e32 v89, v93, v90
	v_cvt_pk_bf16_f32 v89, v89, v89
	v_mfma_f32_16x16x32_bf16 v[208:211], v[76:79], v[16:19], 0
	ds_write_b16 v161, v89 offset:14592
	s_nop 0
	s_nop 3
	v_mfma_f32_16x16x32_bf16 v[212:215], v[76:79], v[20:23], 0
	v_mul_f32_e32 v89, v132, v86
	v_mul_f32_e32 v86, v128, v86
	v_mfma_f32_16x16x32_bf16 v[216:219], v[76:79], v[24:27], 0
	s_nop 0
	s_nop 4
	v_fma_f32 v89, v128, v87, -v89
	v_mfma_f32_16x16x32_bf16 v[220:223], v[76:79], v[28:31], 0
	v_fmac_f32_e32 v86, v132, v87
	v_mfma_f32_16x16x32_bf16 v[76:79], v[76:79], v[48:51], 0
	s_nop 5
	s_nop 7
	v_permlane16_swap_b32_e32 v192, v196
	v_permlane16_swap_b32_e32 v193, v197
	v_permlane16_swap_b32_e32 v194, v198
	v_permlane16_swap_b32_e32 v195, v199
	v_permlane16_swap_b32_e32 v200, v204
	v_permlane16_swap_b32_e32 v201, v205
	v_permlane16_swap_b32_e32 v202, v206
	v_permlane16_swap_b32_e32 v203, v207
	v_permlane16_swap_b32_e32 v208, v212
	v_permlane16_swap_b32_e32 v209, v213
	v_permlane16_swap_b32_e32 v210, v214
	v_permlane16_swap_b32_e32 v211, v215
	v_permlane16_swap_b32_e32 v216, v220
	v_permlane16_swap_b32_e32 v217, v221
	v_permlane16_swap_b32_e32 v218, v222
	v_permlane16_swap_b32_e32 v219, v223
	v_permlane32_swap_b32_e32 v192, v200
	v_permlane32_swap_b32_e32 v193, v201
	v_permlane32_swap_b32_e32 v194, v202
	v_permlane32_swap_b32_e32 v195, v203
	v_permlane32_swap_b32_e32 v196, v204
	v_permlane32_swap_b32_e32 v197, v205
	v_permlane32_swap_b32_e32 v198, v206
	v_permlane32_swap_b32_e32 v199, v207
	v_permlane32_swap_b32_e32 v208, v216
	v_permlane32_swap_b32_e32 v209, v217
	v_permlane32_swap_b32_e32 v210, v218
	v_permlane32_swap_b32_e32 v211, v219
	v_permlane32_swap_b32_e32 v212, v220
	v_permlane32_swap_b32_e32 v213, v221
	v_permlane32_swap_b32_e32 v214, v222
	v_permlane32_swap_b32_e32 v215, v223
	s_waitcnt lgkmcnt(7)
	v_add_f32_e32 v89, v89, v192
	s_waitcnt lgkmcnt(3)
	v_add_f32_e32 v86, v86, v208
	v_cvt_pk_bf16_f32 v87, v89, v86
	ds_write_b32 v149, v87 offset:10240
	v_mul_f32_e32 v87, v132, v86
	v_mul_f32_e32 v86, v128, v86
	v_fma_f32 v87, v128, v89, -v87
	v_fmac_f32_e32 v86, v132, v89
	v_add_f32_e32 v87, v193, v87
	v_add_f32_e32 v86, v209, v86
	v_cvt_pk_bf16_f32 v89, v87, v86
	ds_write_b32 v149, v89 offset:10512
	v_mul_f32_e32 v89, v132, v86
	v_mul_f32_e32 v86, v128, v86
	v_fma_f32 v89, v128, v87, -v89
	v_fmac_f32_e32 v86, v132, v87
	v_add_f32_e32 v89, v194, v89
	v_add_f32_e32 v86, v210, v86
	v_cvt_pk_bf16_f32 v87, v89, v86
	ds_write_b32 v149, v87 offset:10784
	v_mul_f32_e32 v87, v132, v86
	v_mul_f32_e32 v86, v128, v86
	v_fma_f32 v87, v128, v89, -v87
	v_fmac_f32_e32 v86, v132, v89
	v_add_f32_e32 v87, v195, v87
	v_add_f32_e32 v86, v211, v86
	v_cvt_pk_bf16_f32 v89, v87, v86
	ds_write_b32 v149, v89 offset:11056
	v_mul_f32_e32 v89, v132, v86
	v_mul_f32_e32 v86, v128, v86
	v_fma_f32 v89, v128, v87, -v89
	v_fmac_f32_e32 v86, v132, v87
	v_add_f32_e32 v89, v196, v89
	s_waitcnt lgkmcnt(6)
	v_add_f32_e32 v86, v212, v86
	v_cvt_pk_bf16_f32 v87, v89, v86
	ds_write_b32 v149, v87 offset:11328
	v_mul_f32_e32 v87, v132, v86
	v_mul_f32_e32 v86, v128, v86
	v_fma_f32 v87, v128, v89, -v87
	v_fmac_f32_e32 v86, v132, v89
	v_add_f32_e32 v87, v197, v87
	v_add_f32_e32 v86, v213, v86
	v_cvt_pk_bf16_f32 v89, v87, v86
	ds_write_b32 v149, v89 offset:11600
	v_mul_f32_e32 v89, v132, v86
	v_mul_f32_e32 v86, v128, v86
	v_fma_f32 v89, v128, v87, -v89
	v_fmac_f32_e32 v86, v132, v87
	v_add_f32_e32 v89, v198, v89
	v_add_f32_e32 v86, v214, v86
	v_cvt_pk_bf16_f32 v87, v89, v86
	ds_write_b32 v149, v87 offset:11872
	v_mul_f32_e32 v87, v132, v86
	v_mul_f32_e32 v86, v128, v86
	v_fma_f32 v87, v128, v89, -v87
	v_fmac_f32_e32 v86, v132, v89
	v_add_f32_e32 v87, v199, v87
	v_add_f32_e32 v86, v215, v86
	v_cvt_pk_bf16_f32 v89, v87, v86
	ds_write_b32 v149, v89 offset:12144
	v_mul_f32_e32 v89, v132, v86
	v_mul_f32_e32 v86, v128, v86
	v_fma_f32 v89, v128, v87, -v89
	v_fmac_f32_e32 v86, v132, v87
	v_add_f32_e32 v89, v200, v89
	s_waitcnt lgkmcnt(9)
	v_add_f32_e32 v86, v216, v86
	v_cvt_pk_bf16_f32 v87, v89, v86
	ds_write_b32 v149, v87 offset:12416
	v_mul_f32_e32 v87, v132, v86
	v_mul_f32_e32 v86, v128, v86
	v_fma_f32 v87, v128, v89, -v87
	v_fmac_f32_e32 v86, v132, v89
	v_add_f32_e32 v87, v201, v87
	v_add_f32_e32 v86, v217, v86
	v_cvt_pk_bf16_f32 v89, v87, v86
	ds_write_b32 v149, v89 offset:12688
	v_mul_f32_e32 v89, v132, v86
	v_mul_f32_e32 v86, v128, v86
	v_fma_f32 v89, v128, v87, -v89
	v_fmac_f32_e32 v86, v132, v87
	v_add_f32_e32 v89, v202, v89
	v_add_f32_e32 v86, v218, v86
	v_cvt_pk_bf16_f32 v87, v89, v86
	ds_write_b32 v149, v87 offset:12960
	v_mul_f32_e32 v87, v132, v86
	v_mul_f32_e32 v86, v128, v86
	v_fma_f32 v87, v128, v89, -v87
	v_fmac_f32_e32 v86, v132, v89
	v_add_f32_e32 v87, v203, v87
	v_add_f32_e32 v86, v219, v86
	v_cvt_pk_bf16_f32 v89, v87, v86
	ds_write_b32 v149, v89 offset:13232
	v_mul_f32_e32 v89, v132, v86
	v_mul_f32_e32 v86, v128, v86
	v_fma_f32 v89, v128, v87, -v89
	v_fmac_f32_e32 v86, v132, v87
	v_add_f32_e32 v89, v204, v89
	s_waitcnt lgkmcnt(12)
	v_add_f32_e32 v86, v220, v86
	v_cvt_pk_bf16_f32 v87, v89, v86
	ds_write_b32 v149, v87 offset:13504
	v_mul_f32_e32 v87, v132, v86
	v_mul_f32_e32 v86, v128, v86
	v_fma_f32 v87, v128, v89, -v87
	v_fmac_f32_e32 v86, v132, v89
	v_add_f32_e32 v87, v205, v87
	v_add_f32_e32 v86, v221, v86
	v_cvt_pk_bf16_f32 v89, v87, v86
	ds_write_b32 v149, v89 offset:13776
	v_mul_f32_e32 v89, v132, v86
	v_mul_f32_e32 v86, v128, v86
	v_fma_f32 v89, v128, v87, -v89
	v_fmac_f32_e32 v86, v132, v87
	v_add_f32_e32 v89, v206, v89
	v_add_f32_e32 v86, v222, v86
	v_cvt_pk_bf16_f32 v87, v89, v86
	ds_write_b32 v149, v87 offset:14048
	v_mul_f32_e32 v87, v132, v86
	v_mul_f32_e32 v86, v128, v86
	v_fma_f32 v87, v128, v89, -v87
	v_fmac_f32_e32 v86, v132, v89
	v_add_f32_e32 v87, v207, v87
	v_add_f32_e32 v86, v223, v86
	v_cvt_pk_bf16_f32 v89, v87, v86
	ds_write_b32 v149, v89 offset:14320
	s_waitcnt lgkmcnt(0)
	ds_read_b128 v[90:93], v80 offset:10240
	ds_read_b128 v[94:97], v80 offset:10304
	ds_read_b128 v[184:187], v80 offset:10368
	ds_read_b128 v[188:191], v80 offset:10432
	s_waitcnt lgkmcnt(3)
	v_mfma_f32_16x16x32_bf16 v[76:79], v[90:93], v[32:35], v[76:79]
	s_waitcnt lgkmcnt(2)
	v_mfma_f32_16x16x32_bf16 v[76:79], v[94:97], v[36:39], v[76:79]
	s_waitcnt lgkmcnt(1)
	v_mfma_f32_16x16x32_bf16 v[76:79], v[184:187], v[40:43], v[76:79]
	s_waitcnt lgkmcnt(0)
	v_mfma_f32_16x16x32_bf16 v[76:79], v[188:191], v[44:47], v[76:79]
	v_mfma_f32_16x16x32_bf16 v[196:199], v[72:75], v[4:7], 0
	v_mfma_f32_16x16x32_bf16 v[200:203], v[72:75], v[8:11], 0
	s_nop 5
	v_mul_f32_e32 v89, 0x3d122279, v76
	v_fmaak_f32 v89, v76, v89, 0x3f4c422a
	v_mul_f32_e32 v89, v76, v89
	v_mul_f32_e32 v90, 0x3d122279, v77
	v_add_f32_e32 v89, v89, v89
	v_fmaak_f32 v90, v77, v90, 0x3f4c422a
	v_mul_f32_e32 v89, 0xbfb8aa3b, v89
	v_mul_f32_e32 v90, v77, v90
	v_exp_f32_e32 v89, v89
	v_add_f32_e32 v90, v90, v90
	v_mul_f32_e32 v90, 0xbfb8aa3b, v90
	v_exp_f32_e32 v90, v90
	v_add_f32_e32 v89, 1.0, v89
	v_rcp_f32_e32 v89, v89
	v_mfma_f32_16x16x32_bf16 v[204:207], v[72:75], v[12:15], 0
	v_add_f32_e32 v90, 1.0, v90
	v_rcp_f32_e32 v90, v90
	v_mul_f32_e32 v76, v76, v89
	v_cvt_pk_bf16_f32 v76, v76, v76
	ds_write_b16 v160, v76 offset:15104
	v_mul_f32_e32 v76, v77, v90
	v_mul_f32_e32 v77, 0x3d122279, v78
	v_fmaak_f32 v77, v78, v77, 0x3f4c422a
	v_mul_f32_e32 v77, v78, v77
	v_add_f32_e32 v77, v77, v77
	v_mul_f32_e32 v77, 0xbfb8aa3b, v77
	v_exp_f32_e32 v77, v77
	v_mul_f32_e32 v89, 0x3d122279, v79
	v_fmaak_f32 v89, v79, v89, 0x3f4c422a
	v_mul_f32_e32 v89, v79, v89
	v_add_f32_e32 v89, v89, v89
	v_add_f32_e32 v77, 1.0, v77
	v_mul_f32_e32 v89, 0xbfb8aa3b, v89
	v_rcp_f32_e32 v77, v77
	v_exp_f32_e32 v89, v89
	v_cvt_pk_bf16_f32 v76, v76, v76
	ds_write_b16 v160, v76 offset:15136
	v_mul_f32_e32 v76, v78, v77
	v_add_f32_e32 v77, 1.0, v89
	v_rcp_f32_e32 v77, v77
	v_mfma_f32_16x16x32_bf16 v[192:195], v[72:75], v[0:3], 0
	v_cvt_pk_bf16_f32 v76, v76, v76
	ds_write_b16 v160, v76 offset:15168
	v_mul_f32_e32 v76, v79, v77
	v_cvt_pk_bf16_f32 v89, v76, v76
	v_mfma_f32_16x16x32_bf16 v[208:211], v[72:75], v[16:19], 0
	ds_write_b16 v162, v89 offset:14592
	s_nop 0
	s_nop 3
	v_mfma_f32_16x16x32_bf16 v[212:215], v[72:75], v[20:23], 0
	v_mul_f32_e32 v89, v132, v86
	v_mul_f32_e32 v86, v128, v86
	v_mfma_f32_16x16x32_bf16 v[216:219], v[72:75], v[24:27], 0
	s_nop 0
	s_nop 4
	v_fma_f32 v89, v128, v87, -v89
	v_mfma_f32_16x16x32_bf16 v[220:223], v[72:75], v[28:31], 0
	v_fmac_f32_e32 v86, v132, v87
	v_mfma_f32_16x16x32_bf16 v[72:75], v[72:75], v[48:51], 0
	s_nop 5
	s_nop 7
	v_permlane16_swap_b32_e32 v192, v196
	v_permlane16_swap_b32_e32 v193, v197
	v_permlane16_swap_b32_e32 v194, v198
	v_permlane16_swap_b32_e32 v195, v199
	v_permlane16_swap_b32_e32 v200, v204
	v_permlane16_swap_b32_e32 v201, v205
	v_permlane16_swap_b32_e32 v202, v206
	v_permlane16_swap_b32_e32 v203, v207
	v_permlane16_swap_b32_e32 v208, v212
	v_permlane16_swap_b32_e32 v209, v213
	v_permlane16_swap_b32_e32 v210, v214
	v_permlane16_swap_b32_e32 v211, v215
	v_permlane16_swap_b32_e32 v216, v220
	v_permlane16_swap_b32_e32 v217, v221
	v_permlane16_swap_b32_e32 v218, v222
	v_permlane16_swap_b32_e32 v219, v223
	v_permlane32_swap_b32_e32 v192, v200
	v_permlane32_swap_b32_e32 v193, v201
	v_permlane32_swap_b32_e32 v194, v202
	v_permlane32_swap_b32_e32 v195, v203
	v_permlane32_swap_b32_e32 v196, v204
	v_permlane32_swap_b32_e32 v197, v205
	v_permlane32_swap_b32_e32 v198, v206
	v_permlane32_swap_b32_e32 v199, v207
	v_permlane32_swap_b32_e32 v208, v216
	v_permlane32_swap_b32_e32 v209, v217
	v_permlane32_swap_b32_e32 v210, v218
	v_permlane32_swap_b32_e32 v211, v219
	v_permlane32_swap_b32_e32 v212, v220
	v_permlane32_swap_b32_e32 v213, v221
	v_permlane32_swap_b32_e32 v214, v222
	v_permlane32_swap_b32_e32 v215, v223
	s_waitcnt lgkmcnt(7)
	v_add_f32_e32 v76, v89, v192
	s_waitcnt lgkmcnt(3)
	v_add_f32_e32 v86, v86, v208
	v_cvt_pk_bf16_f32 v87, v76, v86
	ds_write_b32 v149, v87 offset:10240
	v_mul_f32_e32 v87, v132, v86
	v_mul_f32_e32 v86, v128, v86
	v_fma_f32 v87, v128, v76, -v87
	v_fmac_f32_e32 v86, v132, v76
	v_add_f32_e32 v77, v193, v87
	v_add_f32_e32 v76, v209, v86
	v_cvt_pk_bf16_f32 v86, v77, v76
	ds_write_b32 v149, v86 offset:10512
	v_mul_f32_e32 v86, v132, v76
	v_mul_f32_e32 v76, v128, v76
	v_fma_f32 v86, v128, v77, -v86
	v_fmac_f32_e32 v76, v132, v77
	v_add_f32_e32 v78, v194, v86
	v_add_f32_e32 v76, v210, v76
	v_cvt_pk_bf16_f32 v77, v78, v76
	ds_write_b32 v149, v77 offset:10784
	v_mul_f32_e32 v77, v132, v76
	v_mul_f32_e32 v76, v128, v76
	v_fma_f32 v77, v128, v78, -v77
	v_fmac_f32_e32 v76, v132, v78
	v_add_f32_e32 v77, v195, v77
	v_add_f32_e32 v76, v211, v76
	v_cvt_pk_bf16_f32 v78, v77, v76
	ds_write_b32 v149, v78 offset:11056
	v_mul_f32_e32 v78, v132, v76
	v_mul_f32_e32 v76, v128, v76
	v_fma_f32 v78, v128, v77, -v78
	v_fmac_f32_e32 v76, v132, v77
	v_add_f32_e32 v78, v196, v78
	s_waitcnt lgkmcnt(6)
	v_add_f32_e32 v76, v212, v76
	v_cvt_pk_bf16_f32 v77, v78, v76
	ds_write_b32 v149, v77 offset:11328
	v_mul_f32_e32 v77, v132, v76
	v_mul_f32_e32 v76, v128, v76
	v_fma_f32 v77, v128, v78, -v77
	v_fmac_f32_e32 v76, v132, v78
	v_add_f32_e32 v77, v197, v77
	v_add_f32_e32 v76, v213, v76
	v_cvt_pk_bf16_f32 v78, v77, v76
	ds_write_b32 v149, v78 offset:11600
	v_mul_f32_e32 v78, v132, v76
	v_mul_f32_e32 v76, v128, v76
	v_fma_f32 v78, v128, v77, -v78
	v_fmac_f32_e32 v76, v132, v77
	v_add_f32_e32 v78, v198, v78
	v_add_f32_e32 v76, v214, v76
	v_cvt_pk_bf16_f32 v77, v78, v76
	ds_write_b32 v149, v77 offset:11872
	v_mul_f32_e32 v77, v132, v76
	v_mul_f32_e32 v76, v128, v76
	v_fma_f32 v77, v128, v78, -v77
	v_fmac_f32_e32 v76, v132, v78
	v_add_f32_e32 v77, v199, v77
	v_add_f32_e32 v76, v215, v76
	v_cvt_pk_bf16_f32 v78, v77, v76
	ds_write_b32 v149, v78 offset:12144
	v_mul_f32_e32 v78, v132, v76
	v_mul_f32_e32 v76, v128, v76
	v_fma_f32 v78, v128, v77, -v78
	v_fmac_f32_e32 v76, v132, v77
	v_add_f32_e32 v78, v200, v78
	s_waitcnt lgkmcnt(9)
	v_add_f32_e32 v76, v216, v76
	v_cvt_pk_bf16_f32 v77, v78, v76
	ds_write_b32 v149, v77 offset:12416
	v_mul_f32_e32 v77, v132, v76
	v_mul_f32_e32 v76, v128, v76
	v_fma_f32 v77, v128, v78, -v77
	v_fmac_f32_e32 v76, v132, v78
	v_add_f32_e32 v77, v201, v77
	v_add_f32_e32 v76, v217, v76
	v_cvt_pk_bf16_f32 v78, v77, v76
	ds_write_b32 v149, v78 offset:12688
	v_mul_f32_e32 v78, v132, v76
	v_mul_f32_e32 v76, v128, v76
	v_fma_f32 v78, v128, v77, -v78
	v_fmac_f32_e32 v76, v132, v77
	v_add_f32_e32 v78, v202, v78
	v_add_f32_e32 v76, v218, v76
	v_cvt_pk_bf16_f32 v77, v78, v76
	ds_write_b32 v149, v77 offset:12960
	v_mul_f32_e32 v77, v132, v76
	v_mul_f32_e32 v76, v128, v76
	v_fma_f32 v77, v128, v78, -v77
	v_fmac_f32_e32 v76, v132, v78
	v_add_f32_e32 v77, v203, v77
	v_add_f32_e32 v76, v219, v76
	v_cvt_pk_bf16_f32 v78, v77, v76
	ds_write_b32 v149, v78 offset:13232
	v_mul_f32_e32 v78, v132, v76
	v_mul_f32_e32 v76, v128, v76
	v_fma_f32 v78, v128, v77, -v78
	v_fmac_f32_e32 v76, v132, v77
	v_add_f32_e32 v78, v204, v78
	s_waitcnt lgkmcnt(12)
	v_add_f32_e32 v76, v220, v76
	v_cvt_pk_bf16_f32 v77, v78, v76
	ds_write_b32 v149, v77 offset:13504
	v_mul_f32_e32 v77, v132, v76
	v_mul_f32_e32 v76, v128, v76
	v_fma_f32 v77, v128, v78, -v77
	v_fmac_f32_e32 v76, v132, v78
	v_add_f32_e32 v77, v205, v77
	v_add_f32_e32 v76, v221, v76
	v_cvt_pk_bf16_f32 v78, v77, v76
	ds_write_b32 v149, v78 offset:13776
	v_mul_f32_e32 v78, v132, v76
	v_mul_f32_e32 v76, v128, v76
	v_fma_f32 v78, v128, v77, -v78
	v_fmac_f32_e32 v76, v132, v77
	v_add_f32_e32 v78, v206, v78
	v_add_f32_e32 v76, v222, v76
	v_cvt_pk_bf16_f32 v77, v78, v76
	ds_write_b32 v149, v77 offset:14048
	v_mul_f32_e32 v77, v132, v76
	v_mul_f32_e32 v76, v128, v76
	v_fma_f32 v77, v128, v78, -v77
	v_fmac_f32_e32 v76, v132, v78
	v_add_f32_e32 v110, v207, v77
	v_add_f32_e32 v111, v223, v76
	v_cvt_pk_bf16_f32 v76, v110, v111
	ds_write_b32 v149, v76 offset:14320
	s_waitcnt lgkmcnt(0)
	ds_read_b128 v[76:79], v80 offset:10240
	ds_read_b128 v[90:93], v80 offset:10304
	ds_read_b128 v[184:187], v80 offset:10368
	ds_read_b128 v[188:191], v80 offset:10432
	s_waitcnt lgkmcnt(3)
	v_mfma_f32_16x16x32_bf16 v[72:75], v[76:79], v[32:35], v[72:75]
	s_waitcnt lgkmcnt(2)
	v_mfma_f32_16x16x32_bf16 v[72:75], v[90:93], v[36:39], v[72:75]
	s_waitcnt lgkmcnt(1)
	v_mfma_f32_16x16x32_bf16 v[72:75], v[184:187], v[40:43], v[72:75]
	s_waitcnt lgkmcnt(0)
	v_mfma_f32_16x16x32_bf16 v[72:75], v[188:191], v[44:47], v[72:75]
	v_mfma_f32_16x16x32_bf16 v[196:199], v[68:71], v[4:7], 0
	v_mfma_f32_16x16x32_bf16 v[200:203], v[68:71], v[8:11], 0
	s_nop 5
	v_mul_f32_e32 v76, 0x3d122279, v72
	v_fmaak_f32 v76, v72, v76, 0x3f4c422a
	v_mul_f32_e32 v76, v72, v76
	v_mul_f32_e32 v77, 0x3d122279, v73
	v_add_f32_e32 v76, v76, v76
	v_fmaak_f32 v77, v73, v77, 0x3f4c422a
	v_mul_f32_e32 v76, 0xbfb8aa3b, v76
	v_mul_f32_e32 v77, v73, v77
	v_exp_f32_e32 v76, v76
	v_add_f32_e32 v77, v77, v77
	v_mul_f32_e32 v77, 0xbfb8aa3b, v77
	v_exp_f32_e32 v77, v77
	v_add_f32_e32 v76, 1.0, v76
	v_rcp_f32_e32 v76, v76
	v_mfma_f32_16x16x32_bf16 v[204:207], v[68:71], v[12:15], 0
	v_add_f32_e32 v77, 1.0, v77
	v_rcp_f32_e32 v77, v77
	v_mul_f32_e32 v72, v72, v76
	v_cvt_pk_bf16_f32 v72, v72, v72
	ds_write_b16 v160, v72 offset:15616
	v_mul_f32_e32 v72, v73, v77
	v_mul_f32_e32 v73, 0x3d122279, v74
	v_fmaak_f32 v73, v74, v73, 0x3f4c422a
	v_mul_f32_e32 v73, v74, v73
	v_add_f32_e32 v73, v73, v73
	v_mul_f32_e32 v73, 0xbfb8aa3b, v73
	v_exp_f32_e32 v73, v73
	v_mul_f32_e32 v76, 0x3d122279, v75
	v_fmaak_f32 v86, v75, v76, 0x3f4c422a
	v_mul_f32_e32 v86, v75, v86
	v_add_f32_e32 v86, v86, v86
	v_add_f32_e32 v73, 1.0, v73
	v_mul_f32_e32 v86, 0xbfb8aa3b, v86
	v_rcp_f32_e32 v73, v73
	v_exp_f32_e32 v86, v86
	v_cvt_pk_bf16_f32 v72, v72, v72
	ds_write_b16 v160, v72 offset:15648
	v_mul_f32_e32 v72, v74, v73
	v_add_f32_e32 v73, 1.0, v86
	v_rcp_f32_e32 v73, v73
	v_mfma_f32_16x16x32_bf16 v[192:195], v[68:71], v[0:3], 0
	v_cvt_pk_bf16_f32 v72, v72, v72
	ds_write_b16 v160, v72 offset:15680
	v_mul_f32_e32 v72, v75, v73
	v_cvt_pk_bf16_f32 v86, v72, v72
	v_mfma_f32_16x16x32_bf16 v[208:211], v[68:71], v[16:19], 0
	ds_write_b16 v163, v86 offset:14592
	s_nop 0
	s_nop 3
	v_mfma_f32_16x16x32_bf16 v[212:215], v[68:71], v[20:23], 0
	v_mfma_f32_16x16x32_bf16 v[216:219], v[68:71], v[24:27], 0
	s_nop 2
	s_nop 2
	v_mul_f32_e32 v81, v132, v111
	v_mfma_f32_16x16x32_bf16 v[220:223], v[68:71], v[28:31], 0
	v_fma_f32 v81, v128, v110, -v81
	v_mfma_f32_16x16x32_bf16 v[68:71], v[68:71], v[48:51], 0
	s_nop 5
	s_nop 7
	v_permlane16_swap_b32_e32 v192, v196
	v_permlane16_swap_b32_e32 v193, v197
	v_permlane16_swap_b32_e32 v194, v198
	v_permlane16_swap_b32_e32 v195, v199
	v_permlane16_swap_b32_e32 v200, v204
	v_permlane16_swap_b32_e32 v201, v205
	v_permlane16_swap_b32_e32 v202, v206
	v_permlane16_swap_b32_e32 v203, v207
	v_permlane16_swap_b32_e32 v208, v212
	v_permlane16_swap_b32_e32 v209, v213
	v_permlane16_swap_b32_e32 v210, v214
	v_permlane16_swap_b32_e32 v211, v215
	v_permlane16_swap_b32_e32 v216, v220
	v_permlane16_swap_b32_e32 v217, v221
	v_permlane16_swap_b32_e32 v218, v222
	v_permlane16_swap_b32_e32 v219, v223
	v_permlane32_swap_b32_e32 v192, v200
	v_permlane32_swap_b32_e32 v193, v201
	v_permlane32_swap_b32_e32 v194, v202
	v_permlane32_swap_b32_e32 v195, v203
	v_permlane32_swap_b32_e32 v196, v204
	v_permlane32_swap_b32_e32 v197, v205
	v_permlane32_swap_b32_e32 v198, v206
	v_permlane32_swap_b32_e32 v199, v207
	v_permlane32_swap_b32_e32 v208, v216
	v_permlane32_swap_b32_e32 v209, v217
	v_permlane32_swap_b32_e32 v210, v218
	v_permlane32_swap_b32_e32 v211, v219
	v_permlane32_swap_b32_e32 v212, v220
	v_permlane32_swap_b32_e32 v213, v221
	v_permlane32_swap_b32_e32 v214, v222
	v_permlane32_swap_b32_e32 v215, v223
	s_waitcnt lgkmcnt(7)
	v_add_f32_e32 v72, v81, v192
	v_mul_f32_e32 v81, v128, v111
	v_fmac_f32_e32 v81, v132, v110
	s_waitcnt lgkmcnt(3)
	v_add_f32_e32 v81, v81, v208
	v_cvt_pk_bf16_f32 v82, v72, v81
	ds_write_b32 v149, v82 offset:10240
	v_mul_f32_e32 v82, v132, v81
	v_mul_f32_e32 v81, v128, v81
	v_fma_f32 v82, v128, v72, -v82
	v_fmac_f32_e32 v81, v132, v72
	v_add_f32_e32 v73, v193, v82
	v_add_f32_e32 v72, v209, v81
	v_cvt_pk_bf16_f32 v81, v73, v72
	ds_write_b32 v149, v81 offset:10512
	v_mul_f32_e32 v81, v132, v72
	v_mul_f32_e32 v72, v128, v72
	v_fma_f32 v81, v128, v73, -v81
	v_fmac_f32_e32 v72, v132, v73
	v_add_f32_e32 v74, v194, v81
	v_add_f32_e32 v72, v210, v72
	v_cvt_pk_bf16_f32 v73, v74, v72
	ds_write_b32 v149, v73 offset:10784
	v_mul_f32_e32 v73, v132, v72
	v_mul_f32_e32 v72, v128, v72
	v_fma_f32 v73, v128, v74, -v73
	v_fmac_f32_e32 v72, v132, v74
	v_add_f32_e32 v73, v195, v73
	v_add_f32_e32 v72, v211, v72
	v_cvt_pk_bf16_f32 v74, v73, v72
	ds_write_b32 v149, v74 offset:11056
	v_mul_f32_e32 v74, v132, v72
	v_mul_f32_e32 v72, v128, v72
	v_fma_f32 v74, v128, v73, -v74
	v_fmac_f32_e32 v72, v132, v73
	v_add_f32_e32 v74, v196, v74
	s_waitcnt lgkmcnt(6)
	v_add_f32_e32 v72, v212, v72
	v_cvt_pk_bf16_f32 v73, v74, v72
	ds_write_b32 v149, v73 offset:11328
	v_mul_f32_e32 v73, v132, v72
	v_mul_f32_e32 v72, v128, v72
	v_fma_f32 v73, v128, v74, -v73
	v_fmac_f32_e32 v72, v132, v74
	v_add_f32_e32 v73, v197, v73
	v_add_f32_e32 v72, v213, v72
	v_cvt_pk_bf16_f32 v74, v73, v72
	ds_write_b32 v149, v74 offset:11600
	v_mul_f32_e32 v74, v132, v72
	v_mul_f32_e32 v72, v128, v72
	v_fma_f32 v74, v128, v73, -v74
	v_fmac_f32_e32 v72, v132, v73
	v_add_f32_e32 v74, v198, v74
	v_add_f32_e32 v72, v214, v72
	v_cvt_pk_bf16_f32 v73, v74, v72
	ds_write_b32 v149, v73 offset:11872
	v_mul_f32_e32 v73, v132, v72
	v_mul_f32_e32 v72, v128, v72
	v_fma_f32 v73, v128, v74, -v73
	v_fmac_f32_e32 v72, v132, v74
	v_add_f32_e32 v73, v199, v73
	v_add_f32_e32 v72, v215, v72
	v_cvt_pk_bf16_f32 v74, v73, v72
	ds_write_b32 v149, v74 offset:12144
	v_mul_f32_e32 v74, v132, v72
	v_mul_f32_e32 v72, v128, v72
	v_fma_f32 v74, v128, v73, -v74
	v_fmac_f32_e32 v72, v132, v73
	v_add_f32_e32 v74, v200, v74
	s_waitcnt lgkmcnt(9)
	v_add_f32_e32 v72, v216, v72
	v_cvt_pk_bf16_f32 v73, v74, v72
	ds_write_b32 v149, v73 offset:12416
	v_mul_f32_e32 v73, v132, v72
	v_mul_f32_e32 v72, v128, v72
	v_fma_f32 v73, v128, v74, -v73
	v_fmac_f32_e32 v72, v132, v74
	v_add_f32_e32 v73, v201, v73
	v_add_f32_e32 v72, v217, v72
	v_cvt_pk_bf16_f32 v74, v73, v72
	ds_write_b32 v149, v74 offset:12688
	v_mul_f32_e32 v74, v132, v72
	v_mul_f32_e32 v72, v128, v72
	v_fma_f32 v74, v128, v73, -v74
	v_fmac_f32_e32 v72, v132, v73
	v_add_f32_e32 v74, v202, v74
	v_add_f32_e32 v72, v218, v72
	v_cvt_pk_bf16_f32 v73, v74, v72
	ds_write_b32 v149, v73 offset:12960
	v_mul_f32_e32 v73, v132, v72
	v_mul_f32_e32 v72, v128, v72
	v_fma_f32 v73, v128, v74, -v73
	v_fmac_f32_e32 v72, v132, v74
	v_add_f32_e32 v75, v203, v73
	v_add_f32_e32 v73, v219, v72
	v_cvt_pk_bf16_f32 v72, v75, v73
	ds_write_b32 v149, v72 offset:13232
	v_mul_f32_e32 v72, v132, v73
	v_mul_f32_e32 v73, v128, v73
	v_fma_f32 v72, v128, v75, -v72
	v_fmac_f32_e32 v73, v132, v75
	v_mov_b32_e32 v74, v204
	s_waitcnt lgkmcnt(12)
	v_mov_b32_e32 v75, v220
	v_pk_add_f32 v[72:73], v[74:75], v[72:73]
	v_mov_b32_e32 v106, v205
	v_cvt_pk_bf16_f32 v74, v72, v73
	ds_write_b32 v149, v74 offset:13504
	v_pk_mul_f32 v[74:75], v[132:133], v[72:73]
	s_nop 0
	v_pk_fma_f32 v[76:77], v[128:129], v[72:73], v[74:75] op_sel:[0, 0, 1] op_sel_hi:[1, 1, 0] neg_lo:[0, 0, 1] neg_hi:[0, 0, 1]
	v_pk_fma_f32 v[72:73], v[128:129], v[72:73], v[74:75] op_sel:[0, 0, 1] op_sel_hi:[1, 1, 0]
	s_nop 0
	v_mov_b32_e32 v77, v73
	v_mov_b32_e32 v107, v221
	v_pk_add_f32 v[72:73], v[106:107], v[76:77]
	s_nop 0
	v_cvt_pk_bf16_f32 v74, v72, v73
	ds_write_b32 v149, v74 offset:13776
	v_pk_mul_f32 v[74:75], v[132:133], v[72:73]
	s_nop 0
	v_pk_fma_f32 v[76:77], v[128:129], v[72:73], v[74:75] op_sel:[0, 0, 1] op_sel_hi:[1, 1, 0] neg_lo:[0, 0, 1] neg_hi:[0, 0, 1]
	v_pk_fma_f32 v[72:73], v[128:129], v[72:73], v[74:75] op_sel:[0, 0, 1] op_sel_hi:[1, 1, 0]
	s_nop 0
	v_mov_b32_e32 v77, v73
	v_mov_b32_e32 v72, v206
	v_mov_b32_e32 v73, v222
	v_pk_add_f32 v[72:73], v[72:73], v[76:77]
	v_mov_b32_e32 v108, v207
	v_cvt_pk_bf16_f32 v74, v72, v73
	ds_write_b32 v149, v74 offset:14048
	v_pk_mul_f32 v[74:75], v[132:133], v[72:73]
	s_nop 0
	v_pk_fma_f32 v[76:77], v[128:129], v[72:73], v[74:75] op_sel:[0, 0, 1] op_sel_hi:[1, 1, 0] neg_lo:[0, 0, 1] neg_hi:[0, 0, 1]
	v_pk_fma_f32 v[72:73], v[128:129], v[72:73], v[74:75] op_sel:[0, 0, 1] op_sel_hi:[1, 1, 0]
	s_nop 0
	v_mov_b32_e32 v77, v73
	v_mov_b32_e32 v109, v223
	v_pk_add_f32 v[86:87], v[108:109], v[76:77]
	s_nop 0
	v_cvt_pk_bf16_f32 v72, v86, v87
	ds_write_b32 v149, v72 offset:14320
	s_waitcnt lgkmcnt(0)
	ds_read_b128 v[72:75], v80 offset:10240
	ds_read_b128 v[76:79], v80 offset:10304
	ds_read_b128 v[184:187], v80 offset:10368
	ds_read_b128 v[188:191], v80 offset:10432
	s_waitcnt lgkmcnt(3)
	v_mfma_f32_16x16x32_bf16 v[68:71], v[72:75], v[32:35], v[68:71]
	s_waitcnt lgkmcnt(2)
	v_mfma_f32_16x16x32_bf16 v[68:71], v[76:79], v[36:39], v[68:71]
	s_waitcnt vmcnt(3)
	v_mov_b64_e32 v[82:83], v[54:55]
	v_mov_b64_e32 v[80:81], v[52:53]
	s_waitcnt lgkmcnt(1)
	v_mfma_f32_16x16x32_bf16 v[68:71], v[184:187], v[40:43], v[68:71]
	s_waitcnt lgkmcnt(0)
	v_mfma_f32_16x16x32_bf16 v[68:71], v[188:191], v[44:47], v[68:71]
	s_waitcnt vmcnt(2)
	v_mov_b64_e32 v[78:79], v[58:59]
	v_mov_b64_e32 v[76:77], v[56:57]
	s_nop 4
	v_mul_f32_e32 v72, 0x3d122279, v68
	v_fmaak_f32 v72, v68, v72, 0x3f4c422a
	v_mul_f32_e32 v72, v68, v72
	v_mul_f32_e32 v73, 0x3d122279, v69
	v_add_f32_e32 v72, v72, v72
	v_fmaak_f32 v73, v69, v73, 0x3f4c422a
	v_mul_f32_e32 v72, 0xbfb8aa3b, v72
	v_mul_f32_e32 v73, v69, v73
	v_exp_f32_e32 v72, v72
	v_add_f32_e32 v73, v73, v73
	v_mul_f32_e32 v73, 0xbfb8aa3b, v73
	v_exp_f32_e32 v73, v73
	v_add_f32_e32 v72, 1.0, v72
	v_rcp_f32_e32 v72, v72
	v_add_f32_e32 v73, 1.0, v73
	v_rcp_f32_e32 v73, v73
	v_mul_f32_e32 v68, v68, v72
	v_cvt_pk_bf16_f32 v68, v68, v68
	ds_write_b16 v160, v68 offset:16128
	v_mul_f32_e32 v68, v69, v73
	v_mul_f32_e32 v69, 0x3d122279, v70
	v_mul_f32_e32 v72, 0x3d122279, v71
	v_fmaak_f32 v69, v70, v69, 0x3f4c422a
	v_fmaak_f32 v72, v71, v72, 0x3f4c422a
	v_mul_f32_e32 v69, v70, v69
	v_mul_f32_e32 v72, v71, v72
	v_add_f32_e32 v69, v69, v69
	v_add_f32_e32 v72, v72, v72
	v_mul_f32_e32 v69, 0xbfb8aa3b, v69
	v_mul_f32_e32 v72, 0xbfb8aa3b, v72
	v_exp_f32_e32 v69, v69
	v_exp_f32_e32 v72, v72
	v_cvt_pk_bf16_f32 v68, v68, v68
	ds_write_b16 v160, v68 offset:16160
	v_add_f32_e32 v69, 1.0, v69
	v_add_f32_e32 v68, 1.0, v72
	v_rcp_f32_e32 v69, v69
	v_rcp_f32_e32 v68, v68
	s_waitcnt vmcnt(1)
	v_mov_b64_e32 v[74:75], v[62:63]
	v_mov_b64_e32 v[72:73], v[60:61]
	v_mul_f32_e32 v69, v70, v69
	v_mul_f32_e32 v68, v71, v68
	v_cvt_pk_bf16_f32 v69, v69, v69
	ds_write_b16 v160, v69 offset:16192
	v_cvt_pk_bf16_f32 v68, v68, v68
	ds_write_b16 v164, v68 offset:14592
	s_waitcnt lgkmcnt(0)
	s_waitcnt vmcnt(0)
	v_mov_b64_e32 v[70:71], v[66:67]
	v_mov_b64_e32 v[68:69], v[64:65]
